# grid barrier: non-leader workgroups poll the cross-XCC release generation directly (skip the per-XCC relay hop); own agent acquire kept
# speedup vs baseline: 1.0003x; 1.0003x over previous
; __device__ __forceinline__ unsigned xb_ld(unsigned* p)              { return __hip_atomic_load(p, __ATOMIC_RELAXED, __HIP_MEMORY_SCOPE_AGENT); }
; __device__ __forceinline__ unsigned xb_add(unsigned* p, unsigned v) { return __hip_atomic_fetch_add(p, v, __ATOMIC_RELAXED, __HIP_MEMORY_SCOPE_AGENT); }
; #define XB_SPIN(cond, bar) do { unsigned _sp = 0; while (cond) { __builtin_amdgcn_s_sleep(1); \
;     if ((++_sp & 255u) == 0u) { if (xb_ld(&(bar)[XB_TMO])) break; if (_sp > XB_SPIN_CAP) { atomicAdd(&(bar)[XB_TMO], 1u); break; } } } } while (0)
; __device__ __forceinline__ void xcd_barrier(const XcdBarrier& b) {
;     ...
;         const unsigned old = xb_add(&bar[XB_XSUB(b.x)], 1u);
;         const unsigned gen = old / nloc;
;         if (old + 1u == (gen + 1u) * nloc) {
;             __builtin_amdgcn_fence(__ATOMIC_RELEASE, "agent");
;             asm volatile("s_waitcnt vmcnt(0)" ::: "memory");
;             const unsigned og = xb_add(&bar[XB_TOP], 1u);
;             const unsigned tg = og / nx;
;             if (og + 1u == (tg + 1u) * nx) xb_add(&bar[XB_TOPGEN], 1u);
;             else XB_SPIN(xb_ld(&bar[XB_TOPGEN]) == tg, bar);
;             __builtin_amdgcn_fence(__ATOMIC_ACQUIRE, "agent");
;             xb_add(&bar[XB_XGEN(b.x)], 1u);
;             asm volatile("s_waitcnt vmcnt(0)" ::: "memory");
;         } else {
;             XB_SPIN(xb_ld(&bar[XB_XGEN(b.x)]) == gen, bar);
.LBB0_233:
	s_or_b64 exec, exec, s[14:15]
	v_cvt_f32_u32_e32 v4, v2
	s_waitcnt vmcnt(0)
	v_readfirstlane_b32 s3, v3
	v_sub_u32_e32 v3, 0, v2
	v_rcp_iflag_f32_e32 v4, v4
	v_add_u32_e32 v5, s3, v1
	v_mul_f32_e32 v4, 0x4f7ffffe, v4
	v_cvt_u32_f32_e32 v4, v4
	v_mul_lo_u32 v1, v3, v4
	v_mul_hi_u32 v1, v4, v1
	v_add_u32_e32 v1, v4, v1
	v_mul_hi_u32 v1, v5, v1
	v_mul_lo_u32 v3, v1, v2
	v_sub_u32_e32 v3, v5, v3
	v_add_u32_e32 v4, 1, v1
	v_cmp_ge_u32_e32 vcc, v3, v2
	s_nop 1
	v_cndmask_b32_e32 v1, v1, v4, vcc
	v_sub_u32_e32 v4, v3, v2
	v_cndmask_b32_e32 v3, v3, v4, vcc
	v_add_u32_e32 v4, 1, v1
	v_cmp_ge_u32_e32 vcc, v3, v2
	v_add_u32_e32 v3, 1, v5
	s_nop 0
	v_cndmask_b32_e32 v1, v1, v4, vcc
	v_mul_lo_u32 v4, v2, v1
	v_add_u32_e32 v2, v4, v2
	v_cmp_ne_u32_e32 vcc, v3, v2
	s_and_saveexec_b64 s[8:9], vcc
	s_xor_b64 s[12:13], exec, s[8:9]
	s_cbranch_execz .LBB0_247
	s_waitcnt lgkmcnt(0)
	v_mov_b32_e32 v0, 0x63000
	global_load_dword v0, v0, s[30:31] offset:1280 sc1
	s_add_u32 s18, s30, 0x63500
	s_addc_u32 s19, s31, 0
	s_waitcnt vmcnt(0)
	v_cmp_eq_u32_e32 vcc, v0, v1
	s_and_saveexec_b64 s[14:15], vcc
	s_cbranch_execz .LBB0_246
	s_add_u32 s16, s30, 0x60200
	s_addc_u32 s17, s31, 0
	s_mov_b32 s3, 1
	s_mov_b64 s[22:23], 0
	v_mov_b32_e32 v0, 0
	s_branch .LBB0_237

; __device__ __forceinline__ unsigned xb_ld(unsigned* p)              { return __hip_atomic_load(p, __ATOMIC_RELAXED, __HIP_MEMORY_SCOPE_AGENT); }
; __device__ __forceinline__ unsigned xb_add(unsigned* p, unsigned v) { return __hip_atomic_fetch_add(p, v, __ATOMIC_RELAXED, __HIP_MEMORY_SCOPE_AGENT); }
; #define XB_SPIN(cond, bar) do { unsigned _sp = 0; while (cond) { __builtin_amdgcn_s_sleep(1); \
;     if ((++_sp & 255u) == 0u) { if (xb_ld(&(bar)[XB_TMO])) break; if (_sp > XB_SPIN_CAP) { atomicAdd(&(bar)[XB_TMO], 1u); break; } } } } while (0)
; __device__ __forceinline__ void xcd_barrier(const XcdBarrier& b) {
;     ...
;         const unsigned old = xb_add(&bar[XB_XSUB(b.x)], 1u);
;         const unsigned gen = old / nloc;
;         if (old + 1u == (gen + 1u) * nloc) {
;             __builtin_amdgcn_fence(__ATOMIC_RELEASE, "agent");
;             asm volatile("s_waitcnt vmcnt(0)" ::: "memory");
;             const unsigned og = xb_add(&bar[XB_TOP], 1u);
;             const unsigned tg = og / nx;
;             if (og + 1u == (tg + 1u) * nx) xb_add(&bar[XB_TOPGEN], 1u);
;             else XB_SPIN(xb_ld(&bar[XB_TOPGEN]) == tg, bar);
;             __builtin_amdgcn_fence(__ATOMIC_ACQUIRE, "agent");
;             xb_add(&bar[XB_XGEN(b.x)], 1u);
;             asm volatile("s_waitcnt vmcnt(0)" ::: "memory");
;         } else {
;             XB_SPIN(xb_ld(&bar[XB_XGEN(b.x)]) == gen, bar);
.LBB0_301:
	s_or_b64 exec, exec, s[12:13]
	v_cvt_f32_u32_e32 v4, v2
	s_waitcnt vmcnt(0)
	v_readfirstlane_b32 s8, v3
	v_sub_u32_e32 v3, 0, v2
	v_rcp_iflag_f32_e32 v4, v4
	v_add_u32_e32 v5, s8, v1
	v_mul_f32_e32 v4, 0x4f7ffffe, v4
	v_cvt_u32_f32_e32 v4, v4
	v_mul_lo_u32 v1, v3, v4
	v_mul_hi_u32 v1, v4, v1
	v_add_u32_e32 v1, v4, v1
	v_mul_hi_u32 v1, v5, v1
	v_mul_lo_u32 v3, v1, v2
	v_sub_u32_e32 v3, v5, v3
	v_add_u32_e32 v4, 1, v1
	v_cmp_ge_u32_e32 vcc, v3, v2
	s_nop 1
	v_cndmask_b32_e32 v1, v1, v4, vcc
	v_sub_u32_e32 v4, v3, v2
	v_cndmask_b32_e32 v3, v3, v4, vcc
	v_add_u32_e32 v4, 1, v1
	v_cmp_ge_u32_e32 vcc, v3, v2
	v_add_u32_e32 v3, 1, v5
	s_nop 0
	v_cndmask_b32_e32 v1, v1, v4, vcc
	v_mul_lo_u32 v4, v2, v1
	v_add_u32_e32 v2, v4, v2
	v_cmp_ne_u32_e32 vcc, v3, v2
	s_and_saveexec_b64 s[8:9], vcc
	s_xor_b64 s[10:11], exec, s[8:9]
	s_cbranch_execz .LBB0_315
	s_waitcnt lgkmcnt(0)
	v_mov_b32_e32 v0, 0x63000
	global_load_dword v0, v0, s[30:31] offset:1280 sc1
	s_add_u32 s16, s30, 0x63500
	s_addc_u32 s17, s31, 0
	s_waitcnt vmcnt(0)
	v_cmp_eq_u32_e32 vcc, v0, v1
	s_and_saveexec_b64 s[12:13], vcc
	s_cbranch_execz .LBB0_314
	s_add_u32 s14, s30, 0x60200
	s_addc_u32 s15, s31, 0
	s_mov_b32 s8, 1
	s_mov_b64 s[18:19], 0
	v_mov_b32_e32 v0, 0
	s_branch .LBB0_305

; __device__ __forceinline__ unsigned xb_ld(unsigned* p)              { return __hip_atomic_load(p, __ATOMIC_RELAXED, __HIP_MEMORY_SCOPE_AGENT); }
; __device__ __forceinline__ unsigned xb_add(unsigned* p, unsigned v) { return __hip_atomic_fetch_add(p, v, __ATOMIC_RELAXED, __HIP_MEMORY_SCOPE_AGENT); }
; #define XB_SPIN(cond, bar) do { unsigned _sp = 0; while (cond) { __builtin_amdgcn_s_sleep(1); \
;     if ((++_sp & 255u) == 0u) { if (xb_ld(&(bar)[XB_TMO])) break; if (_sp > XB_SPIN_CAP) { atomicAdd(&(bar)[XB_TMO], 1u); break; } } } } while (0)
; __device__ __forceinline__ void xcd_barrier(const XcdBarrier& b) {
;     ...
;         const unsigned old = xb_add(&bar[XB_XSUB(b.x)], 1u);
;         const unsigned gen = old / nloc;
;         if (old + 1u == (gen + 1u) * nloc) {
;             __builtin_amdgcn_fence(__ATOMIC_RELEASE, "agent");
;             asm volatile("s_waitcnt vmcnt(0)" ::: "memory");
;             const unsigned og = xb_add(&bar[XB_TOP], 1u);
;             const unsigned tg = og / nx;
;             if (og + 1u == (tg + 1u) * nx) xb_add(&bar[XB_TOPGEN], 1u);
;             else XB_SPIN(xb_ld(&bar[XB_TOPGEN]) == tg, bar);
;             __builtin_amdgcn_fence(__ATOMIC_ACQUIRE, "agent");
;             xb_add(&bar[XB_XGEN(b.x)], 1u);
;             asm volatile("s_waitcnt vmcnt(0)" ::: "memory");
;         } else {
;             XB_SPIN(xb_ld(&bar[XB_XGEN(b.x)]) == gen, bar);
.LBB0_381:
	s_or_b64 exec, exec, s[10:11]
	v_cvt_f32_u32_e32 v4, v2
	s_waitcnt vmcnt(0)
	v_readfirstlane_b32 s6, v3
	v_sub_u32_e32 v3, 0, v2
	v_rcp_iflag_f32_e32 v4, v4
	v_add_u32_e32 v5, s6, v1
	v_mul_f32_e32 v4, 0x4f7ffffe, v4
	v_cvt_u32_f32_e32 v4, v4
	v_mul_lo_u32 v1, v3, v4
	v_mul_hi_u32 v1, v4, v1
	v_add_u32_e32 v1, v4, v1
	v_mul_hi_u32 v1, v5, v1
	v_mul_lo_u32 v3, v1, v2
	v_sub_u32_e32 v3, v5, v3
	v_add_u32_e32 v4, 1, v1
	v_cmp_ge_u32_e32 vcc, v3, v2
	s_nop 1
	v_cndmask_b32_e32 v1, v1, v4, vcc
	v_sub_u32_e32 v4, v3, v2
	v_cndmask_b32_e32 v3, v3, v4, vcc
	v_add_u32_e32 v4, 1, v1
	v_cmp_ge_u32_e32 vcc, v3, v2
	v_add_u32_e32 v3, 1, v5
	s_nop 0
	v_cndmask_b32_e32 v1, v1, v4, vcc
	v_mul_lo_u32 v4, v2, v1
	v_add_u32_e32 v2, v4, v2
	v_cmp_ne_u32_e32 vcc, v3, v2
	s_and_saveexec_b64 s[6:7], vcc
	s_xor_b64 s[6:7], exec, s[6:7]
	s_cbranch_execz .LBB0_395
	s_waitcnt lgkmcnt(0)
	v_mov_b32_e32 v0, 0x63000
	global_load_dword v0, v0, s[30:31] offset:1280 sc1
	s_add_u32 s14, s30, 0x63500
	s_addc_u32 s15, s31, 0
	s_waitcnt vmcnt(0)
	v_cmp_eq_u32_e32 vcc, v0, v1
	s_and_saveexec_b64 s[10:11], vcc
	s_cbranch_execz .LBB0_394
	s_add_u32 s12, s30, 0x60200
	s_addc_u32 s13, s31, 0
	s_mov_b32 s8, 1
	s_mov_b64 s[16:17], 0
	v_mov_b32_e32 v0, 0
	s_branch .LBB0_385

; __device__ __forceinline__ unsigned xb_ld(unsigned* p)              { return __hip_atomic_load(p, __ATOMIC_RELAXED, __HIP_MEMORY_SCOPE_AGENT); }
; __device__ __forceinline__ unsigned xb_add(unsigned* p, unsigned v) { return __hip_atomic_fetch_add(p, v, __ATOMIC_RELAXED, __HIP_MEMORY_SCOPE_AGENT); }
; #define XB_SPIN(cond, bar) do { unsigned _sp = 0; while (cond) { __builtin_amdgcn_s_sleep(1); \
;     if ((++_sp & 255u) == 0u) { if (xb_ld(&(bar)[XB_TMO])) break; if (_sp > XB_SPIN_CAP) { atomicAdd(&(bar)[XB_TMO], 1u); break; } } } } while (0)
; __device__ __forceinline__ void xcd_barrier(const XcdBarrier& b) {
;     ...
;         const unsigned old = xb_add(&bar[XB_XSUB(b.x)], 1u);
;         const unsigned gen = old / nloc;
;         if (old + 1u == (gen + 1u) * nloc) {
;             __builtin_amdgcn_fence(__ATOMIC_RELEASE, "agent");
;             asm volatile("s_waitcnt vmcnt(0)" ::: "memory");
;             const unsigned og = xb_add(&bar[XB_TOP], 1u);
;             const unsigned tg = og / nx;
;             if (og + 1u == (tg + 1u) * nx) xb_add(&bar[XB_TOPGEN], 1u);
;             else XB_SPIN(xb_ld(&bar[XB_TOPGEN]) == tg, bar);
;             __builtin_amdgcn_fence(__ATOMIC_ACQUIRE, "agent");
;             xb_add(&bar[XB_XGEN(b.x)], 1u);
;             asm volatile("s_waitcnt vmcnt(0)" ::: "memory");
;         } else {
;             XB_SPIN(xb_ld(&bar[XB_XGEN(b.x)]) == gen, bar);
.LBB0_439:
	s_or_b64 exec, exec, s[10:11]
	v_cvt_f32_u32_e32 v4, v2
	s_waitcnt vmcnt(0)
	v_readfirstlane_b32 s6, v3
	v_sub_u32_e32 v3, 0, v2
	v_rcp_iflag_f32_e32 v4, v4
	v_add_u32_e32 v5, s6, v1
	v_mul_f32_e32 v4, 0x4f7ffffe, v4
	v_cvt_u32_f32_e32 v4, v4
	v_mul_lo_u32 v1, v3, v4
	v_mul_hi_u32 v1, v4, v1
	v_add_u32_e32 v1, v4, v1
	v_mul_hi_u32 v1, v5, v1
	v_mul_lo_u32 v3, v1, v2
	v_sub_u32_e32 v3, v5, v3
	v_add_u32_e32 v4, 1, v1
	v_cmp_ge_u32_e32 vcc, v3, v2
	s_nop 1
	v_cndmask_b32_e32 v1, v1, v4, vcc
	v_sub_u32_e32 v4, v3, v2
	v_cndmask_b32_e32 v3, v3, v4, vcc
	v_add_u32_e32 v4, 1, v1
	v_cmp_ge_u32_e32 vcc, v3, v2
	v_add_u32_e32 v3, 1, v5
	s_nop 0
	v_cndmask_b32_e32 v1, v1, v4, vcc
	v_mul_lo_u32 v4, v2, v1
	v_add_u32_e32 v2, v4, v2
	v_cmp_ne_u32_e32 vcc, v3, v2
	s_and_saveexec_b64 s[6:7], vcc
	s_xor_b64 s[6:7], exec, s[6:7]
	s_cbranch_execz .LBB0_453
	s_waitcnt lgkmcnt(0)
	v_mov_b32_e32 v0, 0x63000
	global_load_dword v0, v0, s[30:31] offset:1280 sc1
	s_add_u32 s16, s30, 0x63500
	s_addc_u32 s17, s31, 0
	s_waitcnt vmcnt(0)
	v_cmp_eq_u32_e32 vcc, v0, v1
	s_and_saveexec_b64 s[10:11], vcc
	s_cbranch_execz .LBB0_452
	s_add_u32 s14, s30, 0x60200
	s_addc_u32 s15, s31, 0
	s_mov_b32 s8, 1
	s_mov_b64 s[38:39], 0
	v_mov_b32_e32 v0, 0
	s_branch .LBB0_443

; __device__ __forceinline__ unsigned xb_ld(unsigned* p)              { return __hip_atomic_load(p, __ATOMIC_RELAXED, __HIP_MEMORY_SCOPE_AGENT); }
; __device__ __forceinline__ unsigned xb_add(unsigned* p, unsigned v) { return __hip_atomic_fetch_add(p, v, __ATOMIC_RELAXED, __HIP_MEMORY_SCOPE_AGENT); }
; #define XB_SPIN(cond, bar) do { unsigned _sp = 0; while (cond) { __builtin_amdgcn_s_sleep(1); \
;     if ((++_sp & 255u) == 0u) { if (xb_ld(&(bar)[XB_TMO])) break; if (_sp > XB_SPIN_CAP) { atomicAdd(&(bar)[XB_TMO], 1u); break; } } } } while (0)
; __device__ __forceinline__ void xcd_barrier(const XcdBarrier& b) {
;     ...
;         const unsigned old = xb_add(&bar[XB_XSUB(b.x)], 1u);
;         const unsigned gen = old / nloc;
;         if (old + 1u == (gen + 1u) * nloc) {
;             __builtin_amdgcn_fence(__ATOMIC_RELEASE, "agent");
;             asm volatile("s_waitcnt vmcnt(0)" ::: "memory");
;             const unsigned og = xb_add(&bar[XB_TOP], 1u);
;             const unsigned tg = og / nx;
;             if (og + 1u == (tg + 1u) * nx) xb_add(&bar[XB_TOPGEN], 1u);
;             else XB_SPIN(xb_ld(&bar[XB_TOPGEN]) == tg, bar);
;             __builtin_amdgcn_fence(__ATOMIC_ACQUIRE, "agent");
;             xb_add(&bar[XB_XGEN(b.x)], 1u);
;             asm volatile("s_waitcnt vmcnt(0)" ::: "memory");
;         } else {
;             XB_SPIN(xb_ld(&bar[XB_XGEN(b.x)]) == gen, bar);
.LBB0_572:
	s_or_b64 exec, exec, s[10:11]
	v_cvt_f32_u32_e32 v4, v2
	s_waitcnt vmcnt(0)
	v_readfirstlane_b32 s6, v3
	v_sub_u32_e32 v3, 0, v2
	v_rcp_iflag_f32_e32 v4, v4
	v_add_u32_e32 v5, s6, v1
	v_mul_f32_e32 v4, 0x4f7ffffe, v4
	v_cvt_u32_f32_e32 v4, v4
	v_mul_lo_u32 v1, v3, v4
	v_mul_hi_u32 v1, v4, v1
	v_add_u32_e32 v1, v4, v1
	v_mul_hi_u32 v1, v5, v1
	v_mul_lo_u32 v3, v1, v2
	v_sub_u32_e32 v3, v5, v3
	v_add_u32_e32 v4, 1, v1
	v_cmp_ge_u32_e32 vcc, v3, v2
	s_nop 1
	v_cndmask_b32_e32 v1, v1, v4, vcc
	v_sub_u32_e32 v4, v3, v2
	v_cndmask_b32_e32 v3, v3, v4, vcc
	v_add_u32_e32 v4, 1, v1
	v_cmp_ge_u32_e32 vcc, v3, v2
	v_add_u32_e32 v3, 1, v5
	s_nop 0
	v_cndmask_b32_e32 v1, v1, v4, vcc
	v_mul_lo_u32 v4, v2, v1
	v_add_u32_e32 v2, v4, v2
	v_cmp_ne_u32_e32 vcc, v3, v2
	s_and_saveexec_b64 s[6:7], vcc
	s_xor_b64 s[6:7], exec, s[6:7]
	s_cbranch_execz .LBB0_586
	s_waitcnt lgkmcnt(0)
	v_mov_b32_e32 v0, 0x63000
	global_load_dword v0, v0, s[30:31] offset:1280 sc1
	s_add_u32 s48, s30, 0x63500
	s_addc_u32 s49, s31, 0
	s_waitcnt vmcnt(0)
	v_cmp_eq_u32_e32 vcc, v0, v1
	s_and_saveexec_b64 s[10:11], vcc
	s_cbranch_execz .LBB0_585
	s_add_u32 s46, s30, 0x60200
	s_addc_u32 s47, s31, 0
	s_mov_b32 s8, 1
	s_mov_b64 s[50:51], 0
	v_mov_b32_e32 v0, 0
	s_branch .LBB0_576

; __device__ __forceinline__ unsigned xb_ld(unsigned* p)              { return __hip_atomic_load(p, __ATOMIC_RELAXED, __HIP_MEMORY_SCOPE_AGENT); }
; __device__ __forceinline__ unsigned xb_add(unsigned* p, unsigned v) { return __hip_atomic_fetch_add(p, v, __ATOMIC_RELAXED, __HIP_MEMORY_SCOPE_AGENT); }
; #define XB_SPIN(cond, bar) do { unsigned _sp = 0; while (cond) { __builtin_amdgcn_s_sleep(1); \
;     if ((++_sp & 255u) == 0u) { if (xb_ld(&(bar)[XB_TMO])) break; if (_sp > XB_SPIN_CAP) { atomicAdd(&(bar)[XB_TMO], 1u); break; } } } } while (0)
; __device__ __forceinline__ void xcd_barrier(const XcdBarrier& b) {
;     ...
;         const unsigned old = xb_add(&bar[XB_XSUB(b.x)], 1u);
;         const unsigned gen = old / nloc;
;         if (old + 1u == (gen + 1u) * nloc) {
;             __builtin_amdgcn_fence(__ATOMIC_RELEASE, "agent");
;             asm volatile("s_waitcnt vmcnt(0)" ::: "memory");
;             const unsigned og = xb_add(&bar[XB_TOP], 1u);
;             const unsigned tg = og / nx;
;             if (og + 1u == (tg + 1u) * nx) xb_add(&bar[XB_TOPGEN], 1u);
;             else XB_SPIN(xb_ld(&bar[XB_TOPGEN]) == tg, bar);
;             __builtin_amdgcn_fence(__ATOMIC_ACQUIRE, "agent");
;             xb_add(&bar[XB_XGEN(b.x)], 1u);
;             asm volatile("s_waitcnt vmcnt(0)" ::: "memory");
;         } else {
;             XB_SPIN(xb_ld(&bar[XB_XGEN(b.x)]) == gen, bar);
.LBB0_728:
	s_or_b64 exec, exec, s[14:15]
	v_cvt_f32_u32_e32 v4, v2
	s_waitcnt vmcnt(0)
	v_readfirstlane_b32 s8, v3
	v_sub_u32_e32 v3, 0, v2
	v_rcp_iflag_f32_e32 v4, v4
	v_add_u32_e32 v5, s8, v1
	v_mul_f32_e32 v4, 0x4f7ffffe, v4
	v_cvt_u32_f32_e32 v4, v4
	v_mul_lo_u32 v1, v3, v4
	v_mul_hi_u32 v1, v4, v1
	v_add_u32_e32 v1, v4, v1
	v_mul_hi_u32 v1, v5, v1
	v_mul_lo_u32 v3, v1, v2
	v_sub_u32_e32 v3, v5, v3
	v_add_u32_e32 v4, 1, v1
	v_cmp_ge_u32_e32 vcc, v3, v2
	s_nop 1
	v_cndmask_b32_e32 v1, v1, v4, vcc
	v_sub_u32_e32 v4, v3, v2
	v_cndmask_b32_e32 v3, v3, v4, vcc
	v_add_u32_e32 v4, 1, v1
	v_cmp_ge_u32_e32 vcc, v3, v2
	v_add_u32_e32 v3, 1, v5
	s_nop 0
	v_cndmask_b32_e32 v1, v1, v4, vcc
	v_mul_lo_u32 v4, v2, v1
	v_add_u32_e32 v2, v4, v2
	v_cmp_ne_u32_e32 vcc, v3, v2
	s_and_saveexec_b64 s[8:9], vcc
	s_xor_b64 s[10:11], exec, s[8:9]
	s_cbranch_execz .LBB0_742
	s_waitcnt lgkmcnt(0)
	v_mov_b32_e32 v0, 0x63000
	global_load_dword v0, v0, s[30:31] offset:1280 sc1
	s_add_u32 s18, s30, 0x63500
	s_addc_u32 s19, s31, 0
	s_waitcnt vmcnt(0)
	v_cmp_eq_u32_e32 vcc, v0, v1
	s_and_saveexec_b64 s[14:15], vcc
	s_cbranch_execz .LBB0_741
	s_add_u32 s16, s30, 0x60200
	s_addc_u32 s17, s31, 0
	s_mov_b32 s8, 1
	s_mov_b64 s[46:47], 0
	v_mov_b32_e32 v0, 0
	s_branch .LBB0_732

; __device__ __forceinline__ unsigned xb_ld(unsigned* p)              { return __hip_atomic_load(p, __ATOMIC_RELAXED, __HIP_MEMORY_SCOPE_AGENT); }
; __device__ __forceinline__ unsigned xb_add(unsigned* p, unsigned v) { return __hip_atomic_fetch_add(p, v, __ATOMIC_RELAXED, __HIP_MEMORY_SCOPE_AGENT); }
; #define XB_SPIN(cond, bar) do { unsigned _sp = 0; while (cond) { __builtin_amdgcn_s_sleep(1); \
;     if ((++_sp & 255u) == 0u) { if (xb_ld(&(bar)[XB_TMO])) break; if (_sp > XB_SPIN_CAP) { atomicAdd(&(bar)[XB_TMO], 1u); break; } } } } while (0)
; __device__ __forceinline__ void xcd_barrier(const XcdBarrier& b) {
;     ...
;         const unsigned old = xb_add(&bar[XB_XSUB(b.x)], 1u);
;         const unsigned gen = old / nloc;
;         if (old + 1u == (gen + 1u) * nloc) {
;             __builtin_amdgcn_fence(__ATOMIC_RELEASE, "agent");
;             asm volatile("s_waitcnt vmcnt(0)" ::: "memory");
;             const unsigned og = xb_add(&bar[XB_TOP], 1u);
;             const unsigned tg = og / nx;
;             if (og + 1u == (tg + 1u) * nx) xb_add(&bar[XB_TOPGEN], 1u);
;             else XB_SPIN(xb_ld(&bar[XB_TOPGEN]) == tg, bar);
;             __builtin_amdgcn_fence(__ATOMIC_ACQUIRE, "agent");
;             xb_add(&bar[XB_XGEN(b.x)], 1u);
;             asm volatile("s_waitcnt vmcnt(0)" ::: "memory");
;         } else {
;             XB_SPIN(xb_ld(&bar[XB_XGEN(b.x)]) == gen, bar);
.LBB0_847:
	s_or_b64 exec, exec, s[14:15]
	v_cvt_f32_u32_e32 v4, v2
	s_waitcnt vmcnt(0)
	v_readfirstlane_b32 s8, v3
	v_sub_u32_e32 v3, 0, v2
	v_rcp_iflag_f32_e32 v4, v4
	v_add_u32_e32 v5, s8, v1
	v_mul_f32_e32 v4, 0x4f7ffffe, v4
	v_cvt_u32_f32_e32 v4, v4
	v_mul_lo_u32 v1, v3, v4
	v_mul_hi_u32 v1, v4, v1
	v_add_u32_e32 v1, v4, v1
	v_mul_hi_u32 v1, v5, v1
	v_mul_lo_u32 v3, v1, v2
	v_sub_u32_e32 v3, v5, v3
	v_add_u32_e32 v4, 1, v1
	v_cmp_ge_u32_e32 vcc, v3, v2
	s_nop 1
	v_cndmask_b32_e32 v1, v1, v4, vcc
	v_sub_u32_e32 v4, v3, v2
	v_cndmask_b32_e32 v3, v3, v4, vcc
	v_add_u32_e32 v4, 1, v1
	v_cmp_ge_u32_e32 vcc, v3, v2
	v_add_u32_e32 v3, 1, v5
	s_nop 0
	v_cndmask_b32_e32 v1, v1, v4, vcc
	v_mul_lo_u32 v4, v2, v1
	v_add_u32_e32 v2, v4, v2
	v_cmp_ne_u32_e32 vcc, v3, v2
	s_and_saveexec_b64 s[8:9], vcc
	s_xor_b64 s[10:11], exec, s[8:9]
	s_cbranch_execz .LBB0_861
	s_waitcnt lgkmcnt(0)
	v_mov_b32_e32 v0, 0x63000
	global_load_dword v0, v0, s[30:31] offset:1280 sc1
	s_add_u32 s18, s30, 0x63500
	s_addc_u32 s19, s31, 0
	s_waitcnt vmcnt(0)
	v_cmp_eq_u32_e32 vcc, v0, v1
	s_and_saveexec_b64 s[14:15], vcc
	s_cbranch_execz .LBB0_860
	s_add_u32 s16, s30, 0x60200
	s_addc_u32 s17, s31, 0
	s_mov_b32 s8, 1
	s_mov_b64 s[38:39], 0
	v_mov_b32_e32 v0, 0
	s_branch .LBB0_851

; __device__ __forceinline__ unsigned xb_ld(unsigned* p)              { return __hip_atomic_load(p, __ATOMIC_RELAXED, __HIP_MEMORY_SCOPE_AGENT); }
; __device__ __forceinline__ unsigned xb_add(unsigned* p, unsigned v) { return __hip_atomic_fetch_add(p, v, __ATOMIC_RELAXED, __HIP_MEMORY_SCOPE_AGENT); }
; #define XB_SPIN(cond, bar) do { unsigned _sp = 0; while (cond) { __builtin_amdgcn_s_sleep(1); \
;     if ((++_sp & 255u) == 0u) { if (xb_ld(&(bar)[XB_TMO])) break; if (_sp > XB_SPIN_CAP) { atomicAdd(&(bar)[XB_TMO], 1u); break; } } } } while (0)
; __device__ __forceinline__ void xcd_barrier(const XcdBarrier& b) {
;     ...
;         const unsigned old = xb_add(&bar[XB_XSUB(b.x)], 1u);
;         const unsigned gen = old / nloc;
;         if (old + 1u == (gen + 1u) * nloc) {
;             __builtin_amdgcn_fence(__ATOMIC_RELEASE, "agent");
;             asm volatile("s_waitcnt vmcnt(0)" ::: "memory");
;             const unsigned og = xb_add(&bar[XB_TOP], 1u);
;             const unsigned tg = og / nx;
;             if (og + 1u == (tg + 1u) * nx) xb_add(&bar[XB_TOPGEN], 1u);
;             else XB_SPIN(xb_ld(&bar[XB_TOPGEN]) == tg, bar);
;             __builtin_amdgcn_fence(__ATOMIC_ACQUIRE, "agent");
;             xb_add(&bar[XB_XGEN(b.x)], 1u);
;             asm volatile("s_waitcnt vmcnt(0)" ::: "memory");
;         } else {
;             XB_SPIN(xb_ld(&bar[XB_XGEN(b.x)]) == gen, bar);
.LBB0_982:
	s_or_b64 exec, exec, s[14:15]
	v_cvt_f32_u32_e32 v4, v2
	s_waitcnt vmcnt(0)
	v_readfirstlane_b32 s8, v3
	v_sub_u32_e32 v3, 0, v2
	v_rcp_iflag_f32_e32 v4, v4
	v_add_u32_e32 v5, s8, v1
	v_mul_f32_e32 v4, 0x4f7ffffe, v4
	v_cvt_u32_f32_e32 v4, v4
	v_mul_lo_u32 v1, v3, v4
	v_mul_hi_u32 v1, v4, v1
	v_add_u32_e32 v1, v4, v1
	v_mul_hi_u32 v1, v5, v1
	v_mul_lo_u32 v3, v1, v2
	v_sub_u32_e32 v3, v5, v3
	v_add_u32_e32 v4, 1, v1
	v_cmp_ge_u32_e32 vcc, v3, v2
	s_nop 1
	v_cndmask_b32_e32 v1, v1, v4, vcc
	v_sub_u32_e32 v4, v3, v2
	v_cndmask_b32_e32 v3, v3, v4, vcc
	v_add_u32_e32 v4, 1, v1
	v_cmp_ge_u32_e32 vcc, v3, v2
	v_add_u32_e32 v3, 1, v5
	s_nop 0
	v_cndmask_b32_e32 v1, v1, v4, vcc
	v_mul_lo_u32 v4, v2, v1
	v_add_u32_e32 v2, v4, v2
	v_cmp_ne_u32_e32 vcc, v3, v2
	s_and_saveexec_b64 s[8:9], vcc
	s_xor_b64 s[10:11], exec, s[8:9]
	s_cbranch_execz .LBB0_996
	s_waitcnt lgkmcnt(0)
	v_mov_b32_e32 v0, 0x63000
	global_load_dword v0, v0, s[30:31] offset:1280 sc1
	s_add_u32 s18, s30, 0x63500
	s_addc_u32 s19, s31, 0
	s_waitcnt vmcnt(0)
	v_cmp_eq_u32_e32 vcc, v0, v1
	s_and_saveexec_b64 s[14:15], vcc
	s_cbranch_execz .LBB0_995
	s_add_u32 s16, s30, 0x60200
	s_addc_u32 s17, s31, 0
	s_mov_b32 s8, 1
	s_mov_b64 s[20:21], 0
	v_mov_b32_e32 v0, 0
	s_branch .LBB0_986

; __device__ __forceinline__ unsigned xb_ld(unsigned* p)              { return __hip_atomic_load(p, __ATOMIC_RELAXED, __HIP_MEMORY_SCOPE_AGENT); }
; __device__ __forceinline__ unsigned xb_add(unsigned* p, unsigned v) { return __hip_atomic_fetch_add(p, v, __ATOMIC_RELAXED, __HIP_MEMORY_SCOPE_AGENT); }
; #define XB_SPIN(cond, bar) do { unsigned _sp = 0; while (cond) { __builtin_amdgcn_s_sleep(1); \
;     if ((++_sp & 255u) == 0u) { if (xb_ld(&(bar)[XB_TMO])) break; if (_sp > XB_SPIN_CAP) { atomicAdd(&(bar)[XB_TMO], 1u); break; } } } } while (0)
; __device__ __forceinline__ void xcd_barrier(const XcdBarrier& b) {
;     ...
;         const unsigned old = xb_add(&bar[XB_XSUB(b.x)], 1u);
;         const unsigned gen = old / nloc;
;         if (old + 1u == (gen + 1u) * nloc) {
;             __builtin_amdgcn_fence(__ATOMIC_RELEASE, "agent");
;             asm volatile("s_waitcnt vmcnt(0)" ::: "memory");
;             const unsigned og = xb_add(&bar[XB_TOP], 1u);
;             const unsigned tg = og / nx;
;             if (og + 1u == (tg + 1u) * nx) xb_add(&bar[XB_TOPGEN], 1u);
;             else XB_SPIN(xb_ld(&bar[XB_TOPGEN]) == tg, bar);
;             __builtin_amdgcn_fence(__ATOMIC_ACQUIRE, "agent");
;             xb_add(&bar[XB_XGEN(b.x)], 1u);
;             asm volatile("s_waitcnt vmcnt(0)" ::: "memory");
;         } else {
;             XB_SPIN(xb_ld(&bar[XB_XGEN(b.x)]) == gen, bar);
.LBB0_1130:
	s_or_b64 exec, exec, s[6:7]
	v_cvt_f32_u32_e32 v4, v2
	s_waitcnt vmcnt(0)
	v_readfirstlane_b32 s4, v3
	v_sub_u32_e32 v3, 0, v2
	v_rcp_iflag_f32_e32 v4, v4
	v_add_u32_e32 v5, s4, v1
	v_mul_f32_e32 v4, 0x4f7ffffe, v4
	v_cvt_u32_f32_e32 v4, v4
	v_mul_lo_u32 v1, v3, v4
	v_mul_hi_u32 v1, v4, v1
	v_add_u32_e32 v1, v4, v1
	v_mul_hi_u32 v1, v5, v1
	v_mul_lo_u32 v3, v1, v2
	v_sub_u32_e32 v3, v5, v3
	v_add_u32_e32 v4, 1, v1
	v_cmp_ge_u32_e32 vcc, v3, v2
	s_nop 1
	v_cndmask_b32_e32 v1, v1, v4, vcc
	v_sub_u32_e32 v4, v3, v2
	v_cndmask_b32_e32 v3, v3, v4, vcc
	v_add_u32_e32 v4, 1, v1
	v_cmp_ge_u32_e32 vcc, v3, v2
	v_add_u32_e32 v3, 1, v5
	s_nop 0
	v_cndmask_b32_e32 v1, v1, v4, vcc
	v_mul_lo_u32 v4, v2, v1
	v_add_u32_e32 v2, v4, v2
	v_cmp_ne_u32_e32 vcc, v3, v2
	s_and_saveexec_b64 s[4:5], vcc
	s_xor_b64 s[4:5], exec, s[4:5]
	s_cbranch_execz .LBB0_1144
	s_waitcnt lgkmcnt(0)
	v_mov_b32_e32 v0, 0x63000
	global_load_dword v0, v0, s[30:31] offset:1280 sc1
	s_add_u32 s10, s30, 0x63500
	s_addc_u32 s11, s31, 0
	s_waitcnt vmcnt(0)
	v_cmp_eq_u32_e32 vcc, v0, v1
	s_and_saveexec_b64 s[6:7], vcc
	s_cbranch_execz .LBB0_1143
	s_add_u32 s8, s30, 0x60200
	s_addc_u32 s9, s31, 0
	s_mov_b32 s12, 1
	s_mov_b64 s[14:15], 0
	v_mov_b32_e32 v0, 0
	s_branch .LBB0_1134
